# dilated attention: window mask + ALiBi bias per score in f32 (add, fma with |t|, cmp, cndmask: 4 VALU per score instead of 7 integer/convert ops)
# speedup vs baseline: 1.0054x; 1.0054x over previous
; #define MFMA(a, b, c) __builtin_amdgcn_mfma_f32_32x32x16_bf16((a), (b), (c), 0, 0, 0)
; DI int crow(int r, int hi) { return (r & 3) + 8 * (r >> 2) + 4 * hi; }
; DI float xhalf_max(float x) { const auto rr = __builtin_amdgcn_permlane32_swap(__float_as_uint(x), __float_as_uint(x), false, false); return fmaxf(__uint_as_float(rr[0]), __uint_as_float(rr[1])); }
; template <int DQK, int DV, bool BAND> ...
;     ...
;     for (int sub = 0; sub < 2; ++sub) {
;       const int k0 = kt * 64 + sub * 32;
;       if (BAND) { if (k0 > qw0 + 95 || k0 + 31 < qw0 - 64) continue; }
;       f32x16 pacc;
; #pragma unroll
;       for (int r = 0; r < 16; ++r) pacc[r] = 0.f;
;       __builtin_amdgcn_s_setprio(1);
; #pragma unroll
;       for (int d0 = 0; d0 < ND0; ++d0) { const bf16x8 kf = *(const bf16x8*)&Ks[(sub * 32 + r32) * KLD + d0 * 16 + hi * 8]; pacc = MFMA(kf, qf[d0], pacc); }
;       __builtin_amdgcn_s_setprio(0);
;       float mx = -INFINITY;
;       if (BAND) {
; #pragma unroll
;         for (int r = 0; r < 16; ++r) { const int rel = k0 + crow(r, hi) - qi; const int a = rel < 0 ? -rel : rel;
;           const float s = (a <= 64) ? pacc[r] - bias_step * (float)a : -INFINITY; pacc[r] = s; mx = fmaxf(mx, s); }
;       } else {
; #pragma unroll
;         for (int r = 0; r < 16; ++r) mx = fmaxf(mx, pacc[r]);
;       }
;       mx = xhalf_max(mx);
;       if (__builtin_amdgcn_ballot_w64(mx > m_run + 8.f) != 0ull) {
;         const float m_new = fmaxf(m_run, mx); const float m_use = (m_new == -INFINITY) ? 0.f : m_new;
;         const float alpha = __builtin_amdgcn_exp2f(m_run - m_use);
;         l_run *= alpha; m_run = m_new;
;         if (hi == 0) sc[r32] = alpha;
.LBB1_308:
	s_or_b32 s30, s61, s0
	s_or_b32 s28, s30, 31
	v_cmp_le_i32_e32 vcc, s30, v214
	v_cmp_ge_i32_e64 s[40:41], s28, v215
	s_and_b64 s[40:41], vcc, s[40:41]
	s_and_saveexec_b64 s[28:29], s[40:41]
	s_cbranch_execz .LBB1_307
	s_setprio 1
	v_or_b32_e32 v66, s61, v170
	v_mad_u32_u24 v174, v66, s3, v0
	ds_read_b128 v[66:69], v174
	ds_read_b128 v[228:231], v174 offset:32
	s_waitcnt lgkmcnt(1)
	v_mfma_f32_32x32x16_bf16 v[66:81], v[66:69], v[82:85], 0
	s_waitcnt lgkmcnt(0)
	v_mfma_f32_32x32x16_bf16 v[66:81], v[228:231], v[86:89], v[66:81]
	ds_read_b128 v[228:231], v174 offset:64
	s_waitcnt lgkmcnt(0)
	v_mfma_f32_32x32x16_bf16 v[66:81], v[228:231], v[90:93], v[66:81]
	ds_read_b128 v[228:231], v174 offset:96
	s_waitcnt lgkmcnt(0)
	v_mfma_f32_32x32x16_bf16 v[66:81], v[228:231], v[94:97], v[66:81]
	ds_read_b128 v[228:231], v174 offset:128
	s_waitcnt lgkmcnt(0)
	v_mfma_f32_32x32x16_bf16 v[66:81], v[228:231], v[98:101], v[66:81]
	ds_read_b128 v[228:231], v174 offset:160
	s_waitcnt lgkmcnt(0)
	v_mfma_f32_32x32x16_bf16 v[66:81], v[228:231], v[102:105], v[66:81]
	ds_read_b128 v[228:231], v174 offset:192
	s_waitcnt lgkmcnt(0)
	v_mfma_f32_32x32x16_bf16 v[66:81], v[228:231], v[106:109], v[66:81]
	ds_read_b128 v[228:231], v174 offset:224
	s_waitcnt lgkmcnt(0)
	v_mfma_f32_32x32x16_bf16 v[66:81], v[228:231], v[110:113], v[66:81]
	s_setprio 0
	v_add_u32_e32 v174, s30, v217
	v_cvt_f32_i32_e32 v174, v174
	v_mov_b32_e32 v230, 0x42800000
	v_add_f32_e32 v176, 1.0, v174
	v_add_f32_e32 v177, 2.0, v174
	v_add_f32_e32 v229, 0x40400000, v174
	s_nop 4
	v_fma_f32 v66, -v213, |v174|, v66
	v_fma_f32 v67, -v213, |v176|, v67
	v_fma_f32 v68, -v213, |v177|, v68
	v_fma_f32 v69, -v213, |v229|, v69
	v_cmp_le_f32_e64 s[12:13], |v174|, v230
	v_cmp_le_f32_e64 s[14:15], |v176|, v230
	v_cmp_le_f32_e64 s[40:41], |v177|, v230
	v_cmp_le_f32_e64 s[98:99], |v229|, v230
	v_cndmask_b32_e64 v66, v202, v66, s[12:13]
	v_cndmask_b32_e64 v67, v202, v67, s[14:15]
	v_cndmask_b32_e64 v68, v202, v68, s[40:41]
	v_cndmask_b32_e64 v69, v202, v69, s[98:99]
	v_max3_f32 v231, v66, s7, v67
	v_max3_f32 v231, v231, v68, v69
	v_add_f32_e32 v175, 0x41000000, v174
	v_add_f32_e32 v176, 0x41100000, v174
	v_add_f32_e32 v177, 0x41200000, v174
	v_add_f32_e32 v229, 0x41300000, v174
	v_fma_f32 v70, -v213, |v175|, v70
	v_fma_f32 v71, -v213, |v176|, v71
	v_fma_f32 v72, -v213, |v177|, v72
	v_fma_f32 v73, -v213, |v229|, v73
	v_cmp_le_f32_e64 s[12:13], |v175|, v230
	v_cmp_le_f32_e64 s[14:15], |v176|, v230
	v_cmp_le_f32_e64 s[40:41], |v177|, v230
	v_cmp_le_f32_e64 s[98:99], |v229|, v230
	v_cndmask_b32_e64 v70, v202, v70, s[12:13]
	v_cndmask_b32_e64 v71, v202, v71, s[14:15]
	v_cndmask_b32_e64 v72, v202, v72, s[40:41]
	v_cndmask_b32_e64 v73, v202, v73, s[98:99]
	v_max3_f32 v231, v231, v70, v71
	v_max3_f32 v231, v231, v72, v73
	v_add_f32_e32 v175, 0x41800000, v174
	v_add_f32_e32 v176, 0x41880000, v174
	v_add_f32_e32 v177, 0x41900000, v174
	v_add_f32_e32 v229, 0x41980000, v174
	v_fma_f32 v74, -v213, |v175|, v74
	v_fma_f32 v75, -v213, |v176|, v75
	v_fma_f32 v76, -v213, |v177|, v76
	v_fma_f32 v77, -v213, |v229|, v77
	v_cmp_le_f32_e64 s[12:13], |v175|, v230
	v_cmp_le_f32_e64 s[14:15], |v176|, v230
	v_cmp_le_f32_e64 s[40:41], |v177|, v230
	v_cmp_le_f32_e64 s[98:99], |v229|, v230
	v_cndmask_b32_e64 v74, v202, v74, s[12:13]
	v_cndmask_b32_e64 v228, v202, v75, s[14:15]
	v_cndmask_b32_e64 v76, v202, v76, s[40:41]
	v_cndmask_b32_e64 v77, v202, v77, s[98:99]
	v_max3_f32 v231, v231, v74, v228
	v_max3_f32 v231, v231, v76, v77
	v_add_f32_e32 v175, 0x41c00000, v174
	v_add_f32_e32 v176, 0x41c80000, v174
	v_add_f32_e32 v177, 0x41d00000, v174
	v_add_f32_e32 v229, 0x41d80000, v174
	v_fma_f32 v78, -v213, |v175|, v78
	v_fma_f32 v79, -v213, |v176|, v79
	v_fma_f32 v80, -v213, |v177|, v80
	v_fma_f32 v81, -v213, |v229|, v81
	v_cmp_le_f32_e64 s[12:13], |v175|, v230
	v_cmp_le_f32_e64 s[14:15], |v176|, v230
	v_cmp_le_f32_e64 s[40:41], |v177|, v230
	v_cmp_le_f32_e64 s[98:99], |v229|, v230
	v_cndmask_b32_e64 v78, v202, v78, s[12:13]
	v_cndmask_b32_e64 v79, v202, v79, s[14:15]
	v_cndmask_b32_e64 v80, v202, v80, s[40:41]
	v_cndmask_b32_e64 v81, v202, v81, s[98:99]
	v_max3_f32 v231, v231, v78, v79
	v_max3_f32 v75, v231, v80, v81
	v_mov_b32_e32 v174, v75
	s_nop 1
	v_permlane32_swap_b32_e32 v75, v174
	v_max_f32_e32 v174, v174, v174
	v_max_f32_e32 v75, v75, v75
	v_max_f32_e32 v75, v75, v174
	v_add_f32_e32 v174, 0x41000000, v167
	v_cmp_gt_f32_e32 vcc, v75, v174
	s_cbranch_vccz .LBB1_312
	v_max_f32_e32 v75, v75, v75
	v_max_f32_e32 v174, v167, v167
	v_max_f32_e32 v75, v174, v75
	v_cmp_neq_f32_e32 vcc, s7, v75
	s_nop 1
	v_cndmask_b32_e32 v174, 0, v75, vcc
	v_sub_f32_e32 v167, v167, v174
	v_exp_f32_e32 v167, v167
	s_and_saveexec_b64 s[30:31], s[36:37]
	s_cbranch_execz .LBB1_305
	ds_write_b32 v208, v167 offset:34816
	s_branch .LBB1_305
